# attention: static s_setprio 1 for waves 4-7 during the attention units; wait-state pad after QK trimmed to the required 12
# speedup vs baseline: 1.0112x; 1.0112x over previous
.LBB0_502:
	s_xor_b64 s[2:3], s[10:11], -1
	s_and_b64 s[10:11], s[10:11], exec
	v_mbcnt_lo_u32_b32 v0, -1, 0
	v_mbcnt_hi_u32_b32 v0, -1, v0
	s_cselect_b32 s21, s55, s53
	s_bitcmp1_b32 s97, 8
	s_cbranch_scc0 .Latt_prio_lo
	s_setprio 1
.Latt_prio_lo:
	v_add_u32_e32 v5, s97, v0
	v_and_b32_e32 v8, 31, v0
	v_bfe_u32 v9, v0, 5, 1
	v_lshrrev_b32_e32 v3, 1, v0
	v_readfirstlane_b32 s10, v5
	v_bfe_u32 v4, v0, 1, 3
	v_lshlrev_b32_e32 v6, 7, v8
	v_bitop3_b32 v3, v9, v3, 7 bitop3:0x78
	s_ashr_i32 s22, s10, 6
	v_lshl_or_b32 v205, v3, 4, v6
	v_bitop3_b32 v3, v9, v4, 2 bitop3:0x36
	s_lshl_b32 s10, s21, 8
	s_lshl_b32 s11, s22, 5
	v_lshl_or_b32 v206, v3, 4, v6
	v_bitop3_b32 v3, v9, v4, 4 bitop3:0x36
	s_add_i32 s20, s11, s10
	v_lshl_or_b32 v207, v3, 4, v6
	v_bitop3_b32 v3, v9, v4, 6 bitop3:0x36
	v_or_b32_e32 v4, s11, v8
	s_lshl_b32 s11, s22, 2
	v_lshl_or_b32 v208, v3, 4, v6
	v_and_b32_e32 v3, 7, v0
	v_mul_lo_u32 v6, v4, s87
	v_lshlrev_b32_e32 v4, 4, v9
	v_readlane_b32 s12, v251, 34
	v_bfe_u32 v7, v0, 4, 2
	s_and_b32 s11, s11, 4
	v_add3_u32 v209, s12, v6, v4
	v_lshlrev_b32_e32 v6, 3, v0
	v_bitop3_b32 v10, s11, v3, v7 bitop3:0x36
	s_lshl_b32 s10, s22, 9
	v_and_b32_e32 v6, 0x1c0, v6
	v_lshlrev_b32_e32 v10, 3, v10
	v_or3_b32 v210, v10, s10, v6
	v_add_u32_e32 v10, 0xffffffa0, v5
	v_cvt_f32_u32_e32 v11, v10
	s_lshl_b32 s13, s22, 10
	v_or_b32_e32 v6, s13, v6
	v_bitop3_b32 v0, v7, v0, 7 bitop3:0x78
	v_lshl_or_b32 v211, v0, 3, v6
	v_mul_f32_e32 v0, 0x3d800000, v11
	s_mov_b32 s10, 0x800000
	v_cmp_gt_f32_e32 vcc, s10, v0
	v_bitop3_b32 v7, v7, v3, 4 bitop3:0x36
	v_lshlrev_b32_e32 v7, 3, v7
	v_cndmask_b32_e64 v11, 0, 32, vcc
	v_ldexp_f32 v0, v0, v11
	v_log_f32_e32 v0, v0
	s_movk_i32 s10, 0x200
	v_or3_b32 v212, v7, v6, s10
	s_mov_b32 s10, 0x3f317217
	v_mul_f32_e32 v6, 0x3f317217, v0
	v_fma_f32 v6, v0, s10, -v6
	v_fmac_f32_e32 v6, 0x3377d1cf, v0
	s_mov_b32 s10, 0x7f800000
	v_fmac_f32_e32 v6, 0x3f317217, v0
	v_cmp_lt_f32_e64 s[40:41], |v0|, s10
	s_mov_b32 s14, 0x40051592
	s_lshl_b32 s59, s21, 2
	v_cndmask_b32_e64 v0, v0, v6, s[40:41]
	v_mov_b32_e32 v6, 0x41b17218
	v_cndmask_b32_e32 v6, 0, v6, vcc
	v_sub_f32_e32 v0, v0, v6
	v_div_scale_f32 v6, s[10:11], s14, s14, v0
	v_rcp_f32_e32 v7, v6
	s_lshl_b32 s10, s22, 11
	s_add_i32 s61, s10, 0
	s_movk_i32 s10, 0x140
	v_fma_f32 v11, -v6, v7, 1.0
	v_fmac_f32_e32 v7, v11, v7
	v_div_scale_f32 v11, vcc, v0, s14, v0
	v_mul_f32_e32 v12, v11, v7
	v_fma_f32 v13, -v6, v12, v11
	v_fmac_f32_e32 v12, v13, v7
	v_fma_f32 v6, -v6, v12, v11
	v_div_fmas_f32 v6, v6, v7, v12
	v_div_fixup_f32 v0, v6, s14, v0
	v_mul_f32_e32 v0, 0x41800000, v0
	v_cvt_i32_f32_e32 v0, v0
	v_cmp_gt_i32_e64 s[40:41], s10, v5
	s_movk_i32 s10, 0x5f
	v_cmp_lt_i32_e64 s[42:43], s10, v5
	s_add_i32 s10, 0, 0x18000
	s_add_i32 s59, s59, 4
	s_add_i32 s60, s13, 0
	v_lshl_add_u32 v213, v5, 2, s10
	s_lshl_b32 s10, s21, 15
	v_min_i32_e32 v0, 15, v0
	s_add_u32 s10, s62, s10
	v_add_u32_e32 v11, 16, v0
	s_addc_u32 s11, s63, 0
	v_lshlrev_b32_e32 v0, 4, v3
	v_lshl_add_u64 v[134:135], s[10:11], 0, v[0:1]
	v_lshlrev_b32_e32 v6, 6, v5
	v_readlane_b32 s10, v251, 32
	v_ashrrev_i32_e32 v7, 31, v6
	v_readlane_b32 s11, v251, 33
	v_add_u32_e32 v12, s12, v0
	v_readlane_b32 s68, v250, 19
	v_lshl_add_u64 v[136:137], v[6:7], 2, s[10:11]
	s_movk_i32 s10, 0xe0
	v_cmp_gt_u32_e32 vcc, s10, v5
	s_movk_i32 s10, 0x6f
	v_readlane_b32 s78, v250, 29
	v_cndmask_b32_e32 v0, 31, v11, vcc
	v_cmp_lt_u32_e32 vcc, s10, v5
	v_readlane_b32 s79, v250, 30
	v_or_b32_e32 v2, s20, v8
	v_cndmask_b32_e32 v0, v10, v0, vcc
	v_lshl_or_b32 v6, v0, 3, s54
	v_ashrrev_i32_e32 v7, 31, v6
	v_ashrrev_i32_e32 v0, 3, v5
	v_lshl_add_u64 v[138:139], v[6:7], 2, s[78:79]
	v_lshlrev_b32_e32 v140, 6, v0
	v_mul_lo_u32 v6, v0, s87
	v_add_u32_e32 v0, 0x200, v5
	v_ashrrev_i32_e32 v0, 3, v0
	v_lshlrev_b32_e32 v142, 6, v0
	v_mul_lo_u32 v7, v0, s87
	v_add_u32_e32 v0, 0x400, v5
	v_ashrrev_i32_e32 v0, 3, v0
	v_ashrrev_i32_e32 v3, 31, v2
	v_lshlrev_b32_e32 v144, 6, v0
	v_mul_lo_u32 v10, v0, s87
	v_add_u32_e32 v0, 0x600, v5
	v_lshlrev_b64 v[2:3], 11, v[2:3]
	v_ashrrev_i32_e32 v0, 3, v0
	s_lshl_b32 s21, s21, 10
	s_lshl_b32 s10, s22, 7
	v_lshl_add_u64 v[2:3], s[36:37], 0, v[2:3]
	v_lshlrev_b32_e32 v146, 6, v0
	v_mul_lo_u32 v11, v0, s87
	v_lshlrev_b32_e32 v0, 3, v9
	s_add_i32 s10, s21, s10
	v_lshl_add_u64 v[150:151], v[2:3], 0, v[0:1]
	v_lshl_or_b32 v0, v8, 2, s10
	v_mov_b32_e32 v5, v1
	v_sub_u32_e32 v0, v0, v4
	s_mov_b32 s13, 0
	s_or_b32 s86, s20, 31
	s_sub_i32 s20, s20, 63
	v_ashrrev_i32_e32 v141, 31, v140
	v_ashrrev_i32_e32 v143, 31, v142
	v_ashrrev_i32_e32 v145, 31, v144
	v_ashrrev_i32_e32 v147, 31, v146
	v_lshl_add_u64 v[148:149], s[0:1], 0, v[4:5]
	v_add_u32_e32 v214, 0, v0
	s_add_i32 s22, s61, 0x8400
	v_add_u32_e32 v215, v12, v6
	v_add_u32_e32 v216, v12, v7
	v_add_u32_e32 v217, v12, v10
	v_add_u32_e32 v218, v12, v11
	s_mov_b64 s[10:11], -1
	v_readlane_b32 s69, v250, 20
	v_readlane_b32 s70, v250, 21
	v_readlane_b32 s71, v250, 22
	v_readlane_b32 s72, v250, 23
	v_readlane_b32 s73, v250, 24
	v_readlane_b32 s74, v250, 25
	v_readlane_b32 s75, v250, 26
	v_readlane_b32 s76, v250, 27
	v_readlane_b32 s77, v250, 28
	v_readlane_b32 s80, v250, 31
	v_readlane_b32 s81, v250, 32
	v_readlane_b32 s82, v250, 33
	v_readlane_b32 s83, v250, 34
	s_branch .LBB0_504

.LBB0_514:
	s_cmp_gt_i32 s23, s86
	s_cbranch_scc1 .LBB0_510
	s_mul_i32 s13, s27, 0x6000
	s_cmpk_gt_i32 s25, 0x70
	s_cselect_b64 vcc, -1, 0
	s_add_i32 s28, s13, 0x2000
	v_add_u32_e32 v156, s28, v205
	s_bitcmp1_b32 s24, 0
	s_cbranch_scc1 .Latt_k_prefetched
	v_add_u32_e32 v0, s13, v205
	v_add_u32_e32 v82, s13, v206
	v_add_u32_e32 v83, s13, v207
	v_add_u32_e32 v84, s13, v208
	ds_read_b128 v[174:177], v0
	ds_read_b128 v[190:193], v0 offset:4096
	ds_read_b128 v[178:181], v82
	ds_read_b128 v[194:197], v82 offset:4096
	ds_read_b128 v[182:185], v83
	ds_read_b128 v[198:201], v83 offset:4096
	ds_read_b128 v[186:189], v84
	ds_read_b128 v[220:223], v84 offset:4096

.LBB0_517:
	s_nop 8
	v_max3_f32 v0, v82, v66, v83
	v_max3_f32 v157, v67, v84, v68
	v_max3_f32 v0, v0, v85, v69
	v_max3_f32 v157, v157, v86, v70
	v_max3_f32 v0, v0, v87, v71
	v_max3_f32 v157, v157, v88, v72
	v_max3_f32 v0, v0, v89, v73
	v_max3_f32 v157, v157, v90, v74
	v_max3_f32 v0, v0, v91, v75
	v_max3_f32 v157, v157, v92, v76
	v_max3_f32 v0, v0, v93, v77
	v_max3_f32 v157, v157, v94, v78
	v_max3_f32 v0, v0, v95, v79
	v_max3_f32 v157, v157, v96, v80
	v_max3_f32 v0, v0, v97, v81
	v_max_f32_e32 v0, v0, v157
	v_mov_b32_e32 v157, v0
	s_nop 1
	v_permlane32_swap_b32_e32 v0, v157
	s_cmp_eq_u32 s26, 0
	s_cselect_b64 s[44:45], -1, 0
	s_cmp_lg_u32 s26, 0
	v_max_f32_e32 v157, v0, v157
	s_cbranch_scc0 .Latt_first
	s_mov_b32 s13, 0x41000000
	v_cmp_lt_f32_e32 vcc, s13, v157
	s_cbranch_vccz .LBB0_509
	v_max_f32_e32 v0, v157, v157
	v_max_f32_e32 v0, 0, v0
	s_branch .Latt_rescale

.LBB0_529:
	s_setprio 0
	v_readlane_b32 s2, v251, 51
	v_readlane_b32 s3, v251, 52
	v_readlane_b32 s76, v255, 1
	v_readlane_b32 s68, v254, 63
	s_mov_b64 s[0:1], -1
	s_and_b64 vcc, exec, s[2:3]
	s_mov_b64 s[72:73], s[34:35]
	v_readlane_b32 s2, v254, 5
	v_readlane_b32 s86, v251, 40
	v_readlane_b32 s77, v255, 2
	v_readlane_b32 s78, v254, 55
	v_readlane_b32 s71, v254, 56
	v_readlane_b32 s79, v254, 57
	v_readlane_b32 s69, v255, 0
	s_cbranch_vccz .LBB0_551
	v_readlane_b32 s0, v251, 45
	v_readlane_b32 s1, v251, 46
	s_andn2_b64 vcc, exec, s[0:1]
	s_mov_b64 s[4:5], 0
	s_cbranch_vccnz .LBB0_532
	v_mbcnt_lo_u32_b32 v0, -1, 0
	v_mbcnt_hi_u32_b32 v0, -1, v0
	s_nop 0
	v_cmp_eq_u32_e32 vcc, 0, v0
	s_and_b64 s[4:5], vcc, exec
